# in-proj next-tile slice-0 loads: running pointers in free registers, no write-after-write vmcnt guards
# baseline (speedup 1.0000x reference)
; DI unsigned pk2(float a, float b) { f32x2 v = {a, b}; return __builtin_bit_cast(unsigned, __builtin_convertvector(v, bf16x2_t)); }
;   DI static float act(float v) { const float t = fmaxf(v, 0.f); return t * t; }
; #define H_LOAD(KT) do { _Pragma("unroll") for (int i = 0; i < 4; ++i) { ra[i] = *(const u32x4*)(Ap + (size_t)i * 64 * K + (KT) * 64); rb[i] = *(const u32x4*)(Bp + (size_t)i * 64 * K + (KT) * 64); } } while (0)
; template <class Epi>
; DI void gemm_phase512(const bf16_t* A, const bf16_t* Bt, int mtiles, int ntiles, int K, int Kper, int ksplit, const Epi& epi,
;                       unsigned char* smem, int bid, int nb) {
;     ...
;     const int itn = it + nb;
;     const bool more = itn < total;
;     int pmn = pm, pnn = pn; const bf16_t* Apn = Ap; const bf16_t* Bpn = Bp;
;     if (more) H_TILE(itn, pmn, pnn, Apn, Bpn);
;     const int pm_cur = pm, pn_cur = pn;
;     Ap = Apn; Bp = Bpn;
;     H_LOAD(0);
;     {
;       unsigned char* wl = smem + wave * 18432;
;       const int m0 = pm_cur * 256 + wm * 128, n0 = pn_cur * 256 + wn * 64;
;       if constexpr (Epi::kBf16) {
; #pragma unroll
;         for (int ni = 0; ni < 2; ++ni)
; #pragma unroll
;           for (int mi = 0; mi < 4; ++mi)
; #pragma unroll
;             for (int g = 0; g < 4; ++g) {
;               u32x2 w;
;               w[0] = pk2(Epi::act(acc[ni][mi][4 * g]), Epi::act(acc[ni][mi][4 * g + 1]));
;               w[1] = pk2(Epi::act(acc[ni][mi][4 * g + 2]), Epi::act(acc[ni][mi][4 * g + 3]));
;               *(u32x2*)(wl + (mi * 32 + l31) * LDS_STRIDE + (ni * 32 + 8 * g + 4 * hh) * 2) = w;
;             }
;         asm volatile("" ::: "memory");
; #pragma unroll
;         for (int i = 0; i < 16; ++i) {
;           const int row = (lane >> 3) + 8 * i, ch = lane & 7;
;           const u32x4 w = *(const u32x4*)(wl + row * LDS_STRIDE + ch * 16);
;           *(u32x4*)(epi.O + (size_t)(m0 + row) * epi.ldc + n0 + ch * 8) = w;
;         }
.LBB0_126:
	s_mov_b32 s100, 0x20000
	s_mov_b32 s101, 0
	global_load_dwordx4 v[128:131], v[160:161], off
	v_lshl_add_u64 v[246:247], v[160:161], 0, s[100:101]
	global_load_dwordx4 v[132:135], v[246:247], off
	v_lshl_add_u64 v[248:249], v[170:171], 0, s[100:101]
	global_load_dwordx4 v[136:139], v[248:249], off
	v_lshl_add_u64 v[246:247], v[246:247], 0, s[100:101]
	global_load_dwordx4 v[140:143], v[246:247], off
	v_lshl_add_u64 v[248:249], v[248:249], 0, s[100:101]
	global_load_dwordx4 v[144:147], v[248:249], off
	v_lshl_add_u64 v[246:247], v[246:247], 0, s[100:101]
	global_load_dwordx4 v[148:151], v[246:247], off
	global_load_dwordx4 v[156:159], v[170:171], off
	v_lshl_add_u64 v[248:249], v[248:249], 0, s[100:101]
	global_load_dwordx4 v[152:155], v[248:249], off
	v_cvt_pk_bf16_f32 v112, v112, v113
	v_cvt_pk_bf16_f32 v113, v114, v115
	v_cvt_pk_bf16_f32 v114, v116, v117
	v_cvt_pk_bf16_f32 v115, v118, v119
	v_cvt_pk_bf16_f32 v96, v96, v97
	v_cvt_pk_bf16_f32 v97, v98, v99
	v_cvt_pk_bf16_f32 v98, v100, v101
	v_cvt_pk_bf16_f32 v99, v102, v103
	v_add_u32_e32 v100, 0x1000, v197
	v_cvt_pk_bf16_f32 v80, v80, v81
	v_cvt_pk_bf16_f32 v81, v82, v83
	v_cvt_pk_bf16_f32 v82, v84, v85
	v_cvt_pk_bf16_f32 v83, v86, v87
	v_add_u32_e32 v84, 0x2000, v197
	v_cvt_pk_bf16_f32 v64, v64, v65
	v_cvt_pk_bf16_f32 v65, v66, v67
	v_cvt_pk_bf16_f32 v66, v68, v69
	v_cvt_pk_bf16_f32 v67, v70, v71
	v_add_u32_e32 v68, 0x3000, v197
	v_cvt_pk_bf16_f32 v48, v48, v49
	v_cvt_pk_bf16_f32 v49, v50, v51
	v_cvt_pk_bf16_f32 v50, v52, v53
	v_cvt_pk_bf16_f32 v51, v54, v55
	v_cvt_pk_bf16_f32 v32, v32, v33
	v_cvt_pk_bf16_f32 v33, v34, v35
	v_cvt_pk_bf16_f32 v34, v36, v37
	v_cvt_pk_bf16_f32 v35, v38, v39
	v_cvt_pk_bf16_f32 v16, v16, v17
	v_cvt_pk_bf16_f32 v17, v18, v19
	v_cvt_pk_bf16_f32 v18, v20, v21
	v_cvt_pk_bf16_f32 v19, v22, v23
	v_cvt_pk_bf16_f32 v0, v0, v1
	v_cvt_pk_bf16_f32 v1, v2, v3
	v_cvt_pk_bf16_f32 v2, v4, v5
	v_cvt_pk_bf16_f32 v3, v6, v7
	ds_write2_b64 v197, v[112:113], v[114:115] offset1:2
	v_cvt_pk_bf16_f32 v112, v120, v121
	v_cvt_pk_bf16_f32 v113, v122, v123
	v_cvt_pk_bf16_f32 v114, v124, v125
	v_cvt_pk_bf16_f32 v115, v126, v127
	ds_write2_b64 v100, v[96:97], v[98:99] offset0:64 offset1:66
	v_cvt_pk_bf16_f32 v96, v104, v105
	v_cvt_pk_bf16_f32 v97, v106, v107
	v_cvt_pk_bf16_f32 v98, v108, v109
	v_cvt_pk_bf16_f32 v99, v110, v111
	ds_write2_b64 v84, v[80:81], v[82:83] offset0:128 offset1:130
	v_cvt_pk_bf16_f32 v80, v88, v89
	v_cvt_pk_bf16_f32 v81, v90, v91
	v_cvt_pk_bf16_f32 v82, v92, v93
	v_cvt_pk_bf16_f32 v83, v94, v95
	ds_write2_b64 v68, v[64:65], v[66:67] offset0:192 offset1:194
	v_cvt_pk_bf16_f32 v64, v72, v73
	v_cvt_pk_bf16_f32 v65, v74, v75
	v_cvt_pk_bf16_f32 v66, v76, v77
	v_cvt_pk_bf16_f32 v67, v78, v79
	ds_write2_b64 v197, v[48:49], v[50:51] offset0:8 offset1:10
	v_cvt_pk_bf16_f32 v48, v56, v57
	v_cvt_pk_bf16_f32 v49, v58, v59
	v_cvt_pk_bf16_f32 v50, v60, v61
	v_cvt_pk_bf16_f32 v51, v62, v63
	ds_write2_b64 v100, v[32:33], v[34:35] offset0:72 offset1:74
	v_cvt_pk_bf16_f32 v32, v40, v41
	v_cvt_pk_bf16_f32 v33, v42, v43
	v_cvt_pk_bf16_f32 v34, v44, v45
	v_cvt_pk_bf16_f32 v35, v46, v47
	ds_write2_b64 v84, v[16:17], v[18:19] offset0:136 offset1:138
	v_cvt_pk_bf16_f32 v16, v24, v25
	v_cvt_pk_bf16_f32 v17, v26, v27
	v_cvt_pk_bf16_f32 v18, v28, v29
	v_cvt_pk_bf16_f32 v19, v30, v31
	ds_write2_b64 v68, v[0:1], v[2:3] offset0:200 offset1:202
	v_cvt_pk_bf16_f32 v0, v8, v9
	v_cvt_pk_bf16_f32 v1, v10, v11
	v_cvt_pk_bf16_f32 v2, v12, v13
	v_cvt_pk_bf16_f32 v3, v14, v15
	ds_write2_b64 v197, v[112:113], v[114:115] offset0:4 offset1:6
	ds_write2_b64 v100, v[96:97], v[98:99] offset0:68 offset1:70
	ds_write2_b64 v84, v[80:81], v[82:83] offset0:132 offset1:134
	ds_write2_b64 v68, v[64:65], v[66:67] offset0:196 offset1:198
	ds_write2_b64 v197, v[48:49], v[50:51] offset0:12 offset1:14
	ds_write2_b64 v100, v[32:33], v[34:35] offset0:76 offset1:78
	ds_write2_b64 v84, v[16:17], v[18:19] offset0:140 offset1:142
	ds_write2_b64 v68, v[0:1], v[2:3] offset0:204 offset1:206
	v_lshl_add_u32 v0, s24, 8, v173
	v_ashrrev_i32_e32 v1, 31, v0
	v_lshl_or_b32 v12, s25, 8, v174
	v_lshl_add_u64 v[8:9], v[0:1], 1, v[166:167]
	v_or_b32_e32 v4, v12, v175
	v_mad_i64_i32 v[10:11], s[24:25], v4, s20, v[8:9]
	s_mov_b32 s100, 0xd000
	s_mov_b32 s101, 0
	ds_read_b128 v[16:19], v198
	ds_read_b128 v[20:23], v198 offset:1152
	ds_read_b128 v[24:27], v198 offset:2304
	ds_read_b128 v[28:31], v198 offset:3456
	ds_read_b128 v[32:35], v198 offset:4608
	ds_read_b128 v[36:39], v198 offset:5760
	ds_read_b128 v[40:43], v198 offset:6912
	ds_read_b128 v[44:47], v198 offset:8064
	s_waitcnt lgkmcnt(7)
	global_store_dwordx4 v[10:11], v[16:19], off
	v_lshl_add_u64 v[10:11], v[10:11], 0, s[100:101]
	ds_read_b128 v[48:51], v198 offset:9216
	s_waitcnt lgkmcnt(7)
	global_store_dwordx4 v[10:11], v[20:23], off
	v_lshl_add_u64 v[10:11], v[10:11], 0, s[100:101]
	ds_read_b128 v[52:55], v198 offset:10368
	s_waitcnt lgkmcnt(7)
	global_store_dwordx4 v[10:11], v[24:27], off
	v_lshl_add_u64 v[10:11], v[10:11], 0, s[100:101]
	ds_read_b128 v[56:59], v198 offset:11520
	s_waitcnt lgkmcnt(7)
	global_store_dwordx4 v[10:11], v[28:31], off
	v_lshl_add_u64 v[10:11], v[10:11], 0, s[100:101]
	ds_read_b128 v[60:63], v198 offset:12672
	s_waitcnt lgkmcnt(7)
	global_store_dwordx4 v[10:11], v[32:35], off
	v_lshl_add_u64 v[10:11], v[10:11], 0, s[100:101]
	ds_read_b128 v[64:67], v198 offset:13824
	s_waitcnt lgkmcnt(7)
	global_store_dwordx4 v[10:11], v[36:39], off
	v_lshl_add_u64 v[10:11], v[10:11], 0, s[100:101]
	ds_read_b128 v[68:71], v198 offset:14976
	s_waitcnt lgkmcnt(7)
	global_store_dwordx4 v[10:11], v[40:43], off
	v_lshl_add_u64 v[10:11], v[10:11], 0, s[100:101]
	ds_read_b128 v[72:75], v198 offset:16128
	s_waitcnt lgkmcnt(7)
	global_store_dwordx4 v[10:11], v[44:47], off
	v_lshl_add_u64 v[10:11], v[10:11], 0, s[100:101]
	ds_read_b128 v[76:79], v198 offset:17280
	s_waitcnt lgkmcnt(7)
	global_store_dwordx4 v[10:11], v[48:51], off
	v_lshl_add_u64 v[10:11], v[10:11], 0, s[100:101]
	s_waitcnt lgkmcnt(6)
	global_store_dwordx4 v[10:11], v[52:55], off
	v_lshl_add_u64 v[10:11], v[10:11], 0, s[100:101]
	s_waitcnt lgkmcnt(5)
	global_store_dwordx4 v[10:11], v[56:59], off
	v_lshl_add_u64 v[10:11], v[10:11], 0, s[100:101]
	s_waitcnt lgkmcnt(4)
	global_store_dwordx4 v[10:11], v[60:63], off
	v_lshl_add_u64 v[10:11], v[10:11], 0, s[100:101]
	s_waitcnt lgkmcnt(3)
	global_store_dwordx4 v[10:11], v[64:67], off
	v_lshl_add_u64 v[10:11], v[10:11], 0, s[100:101]
	s_waitcnt lgkmcnt(2)
	global_store_dwordx4 v[10:11], v[68:71], off
	v_lshl_add_u64 v[10:11], v[10:11], 0, s[100:101]
	s_waitcnt lgkmcnt(1)
	global_store_dwordx4 v[10:11], v[72:75], off
	v_lshl_add_u64 v[10:11], v[10:11], 0, s[100:101]
	s_waitcnt lgkmcnt(0)
	global_store_dwordx4 v[10:11], v[76:79], off
	s_andn2_b64 vcc, exec, s[2:3]
	s_mov_b32 s24, s22
	s_mov_b32 s25, s26
	s_barrier
	s_cbranch_vccz .LBB0_131
